# gates epilogue: second-half P loads hoisted above first-half compute (v_mov at the old site), on top of the mixer/prologue latency stack
# baseline (speedup 1.0000x reference)
;     __device__ __forceinline__ void operator()(const Acc& acc, const Unit& u, int wr, int wc, int fr, int fq) const {
;     ...
;             const bf16_t* P = (const bf16_t*)p0; const float* gate_b = (const float*)p1; bf16_t* MG = (bf16_t*)p2;
;             const int mc = u.pn * 64 + wc * 16 + 4 * fq;
;             f32x4 gb[4];
; #pragma unroll
;             for (int n = 0; n < 4; ++n) gb[n] = *(const f32x4*)(gate_b + n * DM + mc);
; #pragma unroll
;             for (int ai = 0; ai < 2; ++ai) {
;                 u32x2 pw[1][4][4];
; #pragma unroll
;                 for (int m = 0; m < 4; ++m) { const size_t row = (size_t)(u.pm * BM + ai * HALF + wr * 64 + m * 16 + fr);
; #pragma unroll
;                     for (int gn = 0; gn < 4; ++gn) pw[0][m][gn] = *(const u32x2*)(P + row * 4096 + gn * DM + mc); }
.LBB0_205:
	v_mov_b32_e32 v223, v247
	v_mov_b32_e32 v222, v248
	s_cmp_lt_i32 s47, 2
	s_mov_b64 s[0:1], -1
	s_cbranch_scc1 .LBB0_228
	s_cmp_lt_i32 s47, 3
	s_cbranch_scc1 .LBB0_225
	s_cmp_lg_u32 s47, 3
	s_cbranch_scc0 .LBB0_209
	s_mov_b32 s98, 0x100000
	s_mov_b32 s99, 0
	s_lshl_b32 s0, s84, 6
	s_or_b32 s0, s0, s87
	v_lshl_add_u32 v16, v222, 2, s0
	v_ashrrev_i32_e32 v17, 31, v16
	v_lshl_add_u64 v[0:1], v[16:17], 2, s[16:17]
	global_load_dwordx4 v[12:15], v[0:1], off
	v_add_co_u32_e32 v2, vcc, 0x1000, v0
	s_lshl_b32 s0, s95, 8
	s_nop 0
	v_addc_co_u32_e32 v3, vcc, 0, v1, vcc
	s_add_i32 s0, s0, s57
	global_load_dwordx4 v[8:11], v[2:3], off
	v_add_co_u32_e32 v2, vcc, 0x2000, v0
	v_add_u32_e32 v20, s0, v223
	s_nop 0
	v_addc_co_u32_e32 v3, vcc, 0, v1, vcc
	v_lshlrev_b64 v[16:17], 1, v[16:17]
	v_ashrrev_i32_e32 v21, 31, v20
	v_add_co_u32_e32 v0, vcc, 0x3000, v0
	v_lshl_add_u64 v[18:19], s[14:15], 0, v[16:17]
	v_lshlrev_b64 v[22:23], 13, v[20:21]
	v_addc_co_u32_e32 v1, vcc, 0, v1, vcc
	v_lshl_add_u64 v[22:23], v[18:19], 0, v[22:23]
	global_load_dwordx4 v[4:7], v[2:3], off
	s_movk_i32 s0, 0x1000
	global_load_dwordx4 v[0:3], v[0:1], off
	s_nop 0
	global_load_dwordx2 v[186:187], v[22:23], off
	global_load_dwordx2 v[184:185], v[22:23], off offset:2048
	v_lshl_add_u64 v[230:231], v[22:23], 0, s[98:99]
	global_load_dwordx2 v[192:193], v[230:231], off
	global_load_dwordx2 v[194:195], v[230:231], off offset:2048
	v_add_co_u32_e32 v22, vcc, s0, v22
	v_add_u32_e32 v168, 16, v20
	s_nop 0
	v_addc_co_u32_e32 v23, vcc, 0, v23, vcc
	global_load_dwordx2 v[182:183], v[22:23], off
	global_load_dwordx2 v[180:181], v[22:23], off offset:2048
	v_lshl_add_u64 v[230:231], v[22:23], 0, s[98:99]
	global_load_dwordx2 v[196:197], v[230:231], off
	global_load_dwordx2 v[198:199], v[230:231], off offset:2048
	v_ashrrev_i32_e32 v169, 31, v168
	v_lshlrev_b64 v[22:23], 13, v[168:169]
	v_lshl_add_u64 v[22:23], v[18:19], 0, v[22:23]
	global_load_dwordx2 v[178:179], v[22:23], off
	global_load_dwordx2 v[176:177], v[22:23], off offset:2048
	v_lshl_add_u64 v[230:231], v[22:23], 0, s[98:99]
	global_load_dwordx2 v[200:201], v[230:231], off
	global_load_dwordx2 v[202:203], v[230:231], off offset:2048
	v_add_co_u32_e32 v22, vcc, s0, v22
	v_add_u32_e32 v152, 32, v20
	s_nop 0
	v_addc_co_u32_e32 v23, vcc, 0, v23, vcc
	global_load_dwordx2 v[174:175], v[22:23], off
	global_load_dwordx2 v[172:173], v[22:23], off offset:2048
	v_lshl_add_u64 v[230:231], v[22:23], 0, s[98:99]
	global_load_dwordx2 v[204:205], v[230:231], off
	global_load_dwordx2 v[206:207], v[230:231], off offset:2048
	s_mov_b32 s2, 0xbfb8aa3b
	v_ashrrev_i32_e32 v153, 31, v152
	v_lshlrev_b64 v[22:23], 13, v[152:153]
	v_lshl_add_u64 v[22:23], v[18:19], 0, v[22:23]
	global_load_dwordx2 v[170:171], v[22:23], off
	global_load_dwordx2 v[166:167], v[22:23], off offset:2048
	v_lshl_add_u64 v[230:231], v[22:23], 0, s[98:99]
	global_load_dwordx2 v[208:209], v[230:231], off
	global_load_dwordx2 v[210:211], v[230:231], off offset:2048
	v_add_co_u32_e32 v22, vcc, s0, v22
	v_add_u32_e32 v150, 48, v20
	s_nop 0
	v_addc_co_u32_e32 v23, vcc, 0, v23, vcc
	v_ashrrev_i32_e32 v151, 31, v150
	global_load_dwordx2 v[164:165], v[22:23], off
	global_load_dwordx2 v[160:161], v[22:23], off offset:2048
	v_lshl_add_u64 v[230:231], v[22:23], 0, s[98:99]
	global_load_dwordx2 v[212:213], v[230:231], off
	global_load_dwordx2 v[214:215], v[230:231], off offset:2048
	v_lshlrev_b64 v[22:23], 13, v[150:151]
	v_lshl_add_u64 v[22:23], v[18:19], 0, v[22:23]
	global_load_dwordx2 v[162:163], v[22:23], off
	global_load_dwordx2 v[156:157], v[22:23], off offset:2048
	v_lshl_add_u64 v[230:231], v[22:23], 0, s[98:99]
	global_load_dwordx2 v[216:217], v[230:231], off
	global_load_dwordx2 v[218:219], v[230:231], off offset:2048
	v_add_co_u32_e32 v22, vcc, s0, v22
	v_lshl_add_u64 v[16:17], s[20:21], 0, v[16:17]
	s_nop 0
	v_addc_co_u32_e32 v23, vcc, 0, v23, vcc
	global_load_dwordx2 v[158:159], v[22:23], off
	global_load_dwordx2 v[154:155], v[22:23], off offset:2048
	v_lshl_add_u64 v[230:231], v[22:23], 0, s[98:99]
	global_load_dwordx2 v[220:221], v[230:231], off
	global_load_dwordx2 v[224:225], v[230:231], off offset:2048
	s_waitcnt vmcnt(35)
	v_pk_add_f32 v[188:189], v[142:143], v[12:13]
	s_nop 0
	v_pk_mul_f32 v[188:189], v[188:189], s[2:3] op_sel_hi:[1,0]
	s_waitcnt vmcnt(34)
	v_pk_add_f32 v[190:191], v[134:135], v[8:9]
	v_exp_f32_e32 v188, v188
	v_exp_f32_e32 v189, v189
	v_pk_mul_f32 v[190:191], v[190:191], s[2:3] op_sel_hi:[1,0]
	v_pk_add_f32 v[188:189], v[188:189], 1.0 op_sel_hi:[1,0]
	s_nop 0
	v_rcp_f32_e32 v188, v188
	v_rcp_f32_e32 v189, v189
	v_exp_f32_e32 v190, v190
	v_exp_f32_e32 v191, v191
	s_waitcnt vmcnt(31)
	v_lshlrev_b32_e32 v22, 16, v186
	v_and_b32_e32 v23, 0xffff0000, v186
	v_lshlrev_b32_e32 v24, 16, v187
	v_and_b32_e32 v25, 0xffff0000, v187
	v_pk_add_f32 v[186:187], v[144:145], v[14:15]
	v_pk_fma_f32 v[22:23], v[188:189], v[22:23], 0 op_sel_hi:[1,1,0]
	v_pk_mul_f32 v[186:187], v[186:187], s[2:3] op_sel_hi:[1,0]
	v_pk_add_f32 v[188:189], v[136:137], v[10:11]
	v_exp_f32_e32 v186, v186
	v_exp_f32_e32 v187, v187
	v_pk_mul_f32 v[188:189], v[188:189], s[2:3] op_sel_hi:[1,0]
	v_pk_add_f32 v[190:191], v[190:191], 1.0 op_sel_hi:[1,0]
	v_exp_f32_e32 v188, v188
	v_exp_f32_e32 v189, v189
	v_pk_add_f32 v[186:187], v[186:187], 1.0 op_sel_hi:[1,0]
	v_rcp_f32_e32 v190, v190
	v_rcp_f32_e32 v186, v186
	v_rcp_f32_e32 v187, v187
	v_pk_add_f32 v[188:189], v[188:189], 1.0 op_sel_hi:[1,0]
	v_rcp_f32_e32 v191, v191
	v_rcp_f32_e32 v188, v188
	v_rcp_f32_e32 v189, v189
	v_pk_fma_f32 v[24:25], v[186:187], v[24:25], 0 op_sel_hi:[1,1,0]
	s_waitcnt vmcnt(30)
; __device__ __forceinline__ unsigned cvt_pk_bf16(float lo, float hi) { unsigned r; asm volatile("v_cvt_pk_bf16_f32 %0, %1, %2" : "=v"(r) : "v"(lo), "v"(hi)); return r; }
; __device__ __forceinline__ float bf_lo(unsigned w) { return __uint_as_float(w << 16); }
; __device__ __forceinline__ float bf_hi(unsigned w) { return __uint_as_float(w & 0xffff0000u); }
;     __device__ __forceinline__ void operator()(const Acc& acc, const Unit& u, int wr, int wc, int fr, int fq) const {
;     ...
; #pragma unroll
;                 for (int m = 0; m < 4; ++m) {
;                     const size_t row = (size_t)(u.pm * BM + ai * HALF + wr * 64 + m * 16 + fr);
;                     f32x4 sum = {0.f, 0.f, 0.f, 0.f};
; #pragma unroll
;                     for (int bj = 0; bj < 2; ++bj)
; #pragma unroll
;                         for (int n = 0; n < 2; ++n) {
;                             const int gn = 2 * bj + n;
;                             const u32x2 w2 = pw[0][m][gn];
;                             const f32x4 pv = {bf_lo(w2.x), bf_hi(w2.x), bf_lo(w2.y), bf_hi(w2.y)};
;                             sum += sigmoid4(acc[ai][bj][m][n] + gb[gn]) * pv;
;                         }
;                     u32x2 w; w.x = cvt_pk_bf16(sum[0], sum[1]); w.y = cvt_pk_bf16(sum[2], sum[3]);
;                     *(u32x2*)(MG + row * DM + mc) = w;
	v_lshlrev_b32_e32 v186, 16, v184
	v_and_b32_e32 v187, 0xffff0000, v184
	v_lshlrev_b32_e32 v184, 16, v185
	v_and_b32_e32 v185, 0xffff0000, v185
	v_pk_fma_f32 v[24:25], v[188:189], v[184:185], v[24:25]
	v_pk_add_f32 v[188:189], v[146:147], v[4:5]
	v_pk_fma_f32 v[22:23], v[190:191], v[186:187], v[22:23]
	v_pk_mul_f32 v[188:189], v[188:189], s[2:3] op_sel_hi:[1,0]
	v_pk_add_f32 v[186:187], v[148:149], v[6:7]
	v_exp_f32_e32 v188, v188
	v_exp_f32_e32 v189, v189
	v_pk_mul_f32 v[186:187], v[186:187], s[2:3] op_sel_hi:[1,0]
	s_waitcnt vmcnt(27)
	v_lshlrev_b32_e32 v184, 16, v182
	v_exp_f32_e32 v186, v186
	v_pk_add_f32 v[188:189], v[188:189], 1.0 op_sel_hi:[1,0]
	v_exp_f32_e32 v187, v187
	v_rcp_f32_e32 v188, v188
	v_rcp_f32_e32 v189, v189
	v_and_b32_e32 v185, 0xffff0000, v182
	v_pk_add_f32 v[186:187], v[186:187], 1.0 op_sel_hi:[1,0]
	v_lshlrev_b32_e32 v182, 16, v183
	v_pk_fma_f32 v[22:23], v[188:189], v[184:185], v[22:23]
	v_pk_add_f32 v[184:185], v[140:141], v[2:3]
	v_rcp_f32_e32 v186, v186
	v_pk_mul_f32 v[184:185], v[184:185], s[2:3] op_sel_hi:[1,0]
	v_rcp_f32_e32 v187, v187
	v_exp_f32_e32 v184, v184
	v_exp_f32_e32 v185, v185
	v_and_b32_e32 v183, 0xffff0000, v183
	v_pk_fma_f32 v[24:25], v[186:187], v[182:183], v[24:25]
	v_pk_add_f32 v[186:187], v[138:139], v[0:1]
	v_pk_add_f32 v[184:185], v[184:185], 1.0 op_sel_hi:[1,0]
	v_pk_mul_f32 v[186:187], v[186:187], s[2:3] op_sel_hi:[1,0]
	v_rcp_f32_e32 v184, v184
	v_rcp_f32_e32 v185, v185
	v_exp_f32_e32 v186, v186
	v_exp_f32_e32 v187, v187
	s_waitcnt vmcnt(26)
	v_lshlrev_b32_e32 v182, 16, v180
	v_and_b32_e32 v183, 0xffff0000, v180
	v_lshlrev_b32_e32 v180, 16, v181
	v_and_b32_e32 v181, 0xffff0000, v181
	v_pk_fma_f32 v[24:25], v[184:185], v[180:181], v[24:25]
	v_pk_add_f32 v[180:181], v[126:127], v[12:13]
	v_pk_add_f32 v[186:187], v[186:187], 1.0 op_sel_hi:[1,0]
	v_pk_mul_f32 v[180:181], v[180:181], s[2:3] op_sel_hi:[1,0]
	v_rcp_f32_e32 v186, v186
	v_exp_f32_e32 v180, v180
	v_exp_f32_e32 v181, v181
	v_rcp_f32_e32 v187, v187
	v_pk_add_f32 v[184:185], v[80:81], v[14:15]
	v_pk_add_f32 v[188:189], v[70:71], v[8:9]
	v_pk_add_f32 v[180:181], v[180:181], 1.0 op_sel_hi:[1,0]
	v_pk_fma_f32 v[22:23], v[186:187], v[182:183], v[22:23]
	v_rcp_f32_e32 v180, v180
	v_rcp_f32_e32 v181, v181
	v_cvt_pk_bf16_f32 v22, v22, v23
	v_cvt_pk_bf16_f32 v23, v24, v25
	v_lshlrev_b64 v[24:25], 11, v[20:21]
	v_lshl_add_u64 v[24:25], v[16:17], 0, v[24:25]
	global_store_dwordx2 v[24:25], v[22:23], off
	s_waitcnt vmcnt(24)
	v_lshlrev_b32_e32 v22, 16, v178
	v_and_b32_e32 v23, 0xffff0000, v178
	v_lshlrev_b32_e32 v24, 16, v179
	v_and_b32_e32 v25, 0xffff0000, v179
	v_pk_add_f32 v[178:179], v[128:129], v[14:15]
	v_pk_fma_f32 v[22:23], v[180:181], v[22:23], 0 op_sel_hi:[1,1,0]
	v_pk_mul_f32 v[178:179], v[178:179], s[2:3] op_sel_hi:[1,0]
	v_pk_add_f32 v[180:181], v[120:121], v[10:11]
	v_pk_add_f32 v[182:183], v[118:119], v[8:9]
	v_exp_f32_e32 v178, v178
	v_exp_f32_e32 v179, v179
	v_pk_mul_f32 v[180:181], v[180:181], s[2:3] op_sel_hi:[1,0]
	v_pk_mul_f32 v[182:183], v[182:183], s[2:3] op_sel_hi:[1,0]
	v_exp_f32_e32 v180, v180
	v_exp_f32_e32 v182, v182
	v_exp_f32_e32 v183, v183
	v_exp_f32_e32 v181, v181
	v_pk_add_f32 v[178:179], v[178:179], 1.0 op_sel_hi:[1,0]
	v_pk_add_f32 v[186:187], v[78:79], v[12:13]
	v_rcp_f32_e32 v178, v178
	v_rcp_f32_e32 v179, v179
	v_pk_add_f32 v[180:181], v[180:181], 1.0 op_sel_hi:[1,0]
	v_pk_add_f32 v[182:183], v[182:183], 1.0 op_sel_hi:[1,0]
	v_rcp_f32_e32 v180, v180
	v_rcp_f32_e32 v182, v182
	v_rcp_f32_e32 v183, v183
	v_rcp_f32_e32 v181, v181
	v_pk_fma_f32 v[24:25], v[178:179], v[24:25], 0 op_sel_hi:[1,1,0]
	s_waitcnt vmcnt(23)
	v_lshlrev_b32_e32 v178, 16, v176
	v_and_b32_e32 v179, 0xffff0000, v176
	v_lshlrev_b32_e32 v176, 16, v177
	v_and_b32_e32 v177, 0xffff0000, v177
	v_pk_fma_f32 v[22:23], v[182:183], v[178:179], v[22:23]
	v_pk_fma_f32 v[24:25], v[180:181], v[176:177], v[24:25]
	v_pk_add_f32 v[178:179], v[132:133], v[6:7]
	v_pk_add_f32 v[180:181], v[130:131], v[4:5]
	v_pk_mul_f32 v[178:179], v[178:179], s[2:3] op_sel_hi:[1,0]
	v_pk_mul_f32 v[180:181], v[180:181], s[2:3] op_sel_hi:[1,0]
	v_exp_f32_e32 v178, v178
	v_exp_f32_e32 v180, v180
	v_exp_f32_e32 v181, v181
	v_exp_f32_e32 v179, v179
	s_waitcnt vmcnt(20)
	v_lshlrev_b32_e32 v176, 16, v174
	v_and_b32_e32 v177, 0xffff0000, v174
	v_pk_add_f32 v[180:181], v[180:181], 1.0 op_sel_hi:[1,0]
	v_pk_add_f32 v[178:179], v[178:179], 1.0 op_sel_hi:[1,0]
	v_rcp_f32_e32 v180, v180
	v_rcp_f32_e32 v181, v181
	v_rcp_f32_e32 v178, v178
	v_rcp_f32_e32 v179, v179
	v_lshlrev_b32_e32 v174, 16, v175
	v_and_b32_e32 v175, 0xffff0000, v175
	v_pk_fma_f32 v[22:23], v[180:181], v[176:177], v[22:23]
	v_pk_fma_f32 v[24:25], v[178:179], v[174:175], v[24:25]
	v_pk_add_f32 v[176:177], v[124:125], v[2:3]
	v_pk_add_f32 v[178:179], v[122:123], v[0:1]
	v_pk_mul_f32 v[176:177], v[176:177], s[2:3] op_sel_hi:[1,0]
	v_pk_mul_f32 v[178:179], v[178:179], s[2:3] op_sel_hi:[1,0]
	v_exp_f32_e32 v176, v176
	v_exp_f32_e32 v178, v178
	v_exp_f32_e32 v179, v179
	v_exp_f32_e32 v177, v177
	s_waitcnt vmcnt(19)
	v_lshlrev_b32_e32 v174, 16, v172
	v_and_b32_e32 v175, 0xffff0000, v172
	v_pk_add_f32 v[178:179], v[178:179], 1.0 op_sel_hi:[1,0]
	v_pk_add_f32 v[176:177], v[176:177], 1.0 op_sel_hi:[1,0]
	v_rcp_f32_e32 v178, v178
	v_rcp_f32_e32 v179, v179
	v_rcp_f32_e32 v176, v176
	v_rcp_f32_e32 v177, v177
	v_lshlrev_b32_e32 v172, 16, v173
	v_and_b32_e32 v173, 0xffff0000, v173
	v_pk_fma_f32 v[22:23], v[178:179], v[174:175], v[22:23]
	v_pk_fma_f32 v[24:25], v[176:177], v[172:173], v[24:25]
	v_cvt_pk_bf16_f32 v22, v22, v23
	v_pk_add_f32 v[172:173], v[102:103], v[8:9]
	v_cvt_pk_bf16_f32 v23, v24, v25
	v_lshlrev_b64 v[24:25], 11, v[168:169]
	v_lshl_add_u64 v[24:25], v[16:17], 0, v[24:25]
	global_store_dwordx2 v[24:25], v[22:23], off
	s_waitcnt vmcnt(17)
; __device__ __forceinline__ unsigned cvt_pk_bf16(float lo, float hi) { unsigned r; asm volatile("v_cvt_pk_bf16_f32 %0, %1, %2" : "=v"(r) : "v"(lo), "v"(hi)); return r; }
; __device__ __forceinline__ float bf_lo(unsigned w) { return __uint_as_float(w << 16); }
; __device__ __forceinline__ float bf_hi(unsigned w) { return __uint_as_float(w & 0xffff0000u); }
;     __device__ __forceinline__ void operator()(const Acc& acc, const Unit& u, int wr, int wc, int fr, int fq) const {
;     ...
; #pragma unroll
;                 for (int m = 0; m < 4; ++m) {
;                     const size_t row = (size_t)(u.pm * BM + ai * HALF + wr * 64 + m * 16 + fr);
;                     f32x4 sum = {0.f, 0.f, 0.f, 0.f};
; #pragma unroll
;                     for (int bj = 0; bj < 2; ++bj)
; #pragma unroll
;                         for (int n = 0; n < 2; ++n) {
;                             const int gn = 2 * bj + n;
;                             const u32x2 w2 = pw[0][m][gn];
;                             const f32x4 pv = {bf_lo(w2.x), bf_hi(w2.x), bf_lo(w2.y), bf_hi(w2.y)};
;                             sum += sigmoid4(acc[ai][bj][m][n] + gb[gn]) * pv;
;                         }
;                     u32x2 w; w.x = cvt_pk_bf16(sum[0], sum[1]); w.y = cvt_pk_bf16(sum[2], sum[3]);
;                     *(u32x2*)(MG + row * DM + mc) = w;
	v_lshlrev_b32_e32 v22, 16, v170
	v_and_b32_e32 v23, 0xffff0000, v170
	v_lshlrev_b32_e32 v24, 16, v171
	v_and_b32_e32 v25, 0xffff0000, v171
	v_pk_add_f32 v[170:171], v[110:111], v[12:13]
	v_pk_add_f32 v[168:169], v[112:113], v[14:15]
	v_pk_mul_f32 v[170:171], v[170:171], s[2:3] op_sel_hi:[1,0]
	v_pk_mul_f32 v[168:169], v[168:169], s[2:3] op_sel_hi:[1,0]
	v_exp_f32_e32 v170, v170
	v_exp_f32_e32 v171, v171
	v_exp_f32_e32 v168, v168
	v_exp_f32_e32 v169, v169
	v_pk_mul_f32 v[172:173], v[172:173], s[2:3] op_sel_hi:[1,0]
	v_pk_add_f32 v[170:171], v[170:171], 1.0 op_sel_hi:[1,0]
	v_exp_f32_e32 v172, v172
	v_rcp_f32_e32 v170, v170
	v_rcp_f32_e32 v171, v171
	v_pk_add_f32 v[168:169], v[168:169], 1.0 op_sel_hi:[1,0]
	v_exp_f32_e32 v173, v173
	v_rcp_f32_e32 v168, v168
	v_pk_fma_f32 v[22:23], v[170:171], v[22:23], 0 op_sel_hi:[1,1,0]
	v_pk_add_f32 v[170:171], v[104:105], v[10:11]
	v_rcp_f32_e32 v169, v169
	v_pk_mul_f32 v[170:171], v[170:171], s[2:3] op_sel_hi:[1,0]
	v_pk_add_f32 v[172:173], v[172:173], 1.0 op_sel_hi:[1,0]
	v_exp_f32_e32 v170, v170
	v_exp_f32_e32 v171, v171
	v_pk_fma_f32 v[24:25], v[168:169], v[24:25], 0 op_sel_hi:[1,1,0]
	s_waitcnt vmcnt(16)
	v_lshlrev_b32_e32 v168, 16, v166
	v_and_b32_e32 v169, 0xffff0000, v166
	v_pk_add_f32 v[170:171], v[170:171], 1.0 op_sel_hi:[1,0]
	v_lshlrev_b32_e32 v166, 16, v167
	v_rcp_f32_e32 v170, v170
	v_rcp_f32_e32 v171, v171
	v_and_b32_e32 v167, 0xffff0000, v167
	v_rcp_f32_e32 v172, v172
	v_rcp_f32_e32 v173, v173
	v_pk_fma_f32 v[24:25], v[170:171], v[166:167], v[24:25]
	v_pk_add_f32 v[170:171], v[114:115], v[4:5]
	s_waitcnt vmcnt(13)
	v_lshlrev_b32_e32 v166, 16, v164
	v_pk_mul_f32 v[170:171], v[170:171], s[2:3] op_sel_hi:[1,0]
	v_pk_fma_f32 v[22:23], v[172:173], v[168:169], v[22:23]
	v_exp_f32_e32 v170, v170
	v_exp_f32_e32 v171, v171
	v_pk_add_f32 v[168:169], v[116:117], v[6:7]
	v_and_b32_e32 v167, 0xffff0000, v164
	v_pk_mul_f32 v[168:169], v[168:169], s[2:3] op_sel_hi:[1,0]
	v_pk_add_f32 v[170:171], v[170:171], 1.0 op_sel_hi:[1,0]
	v_exp_f32_e32 v168, v168
	v_rcp_f32_e32 v170, v170
	v_rcp_f32_e32 v171, v171
	v_exp_f32_e32 v169, v169
	v_lshlrev_b32_e32 v164, 16, v165
	v_and_b32_e32 v165, 0xffff0000, v165
	v_pk_fma_f32 v[22:23], v[170:171], v[166:167], v[22:23]
	v_pk_add_f32 v[166:167], v[108:109], v[2:3]
	v_pk_add_f32 v[168:169], v[168:169], 1.0 op_sel_hi:[1,0]
	v_pk_mul_f32 v[166:167], v[166:167], s[2:3] op_sel_hi:[1,0]
	v_rcp_f32_e32 v168, v168
	v_exp_f32_e32 v166, v166
	v_exp_f32_e32 v167, v167
	v_rcp_f32_e32 v169, v169
	v_add_u32_e32 v174, 0x80, v20
	v_ashrrev_i32_e32 v175, 31, v174
	v_pk_add_f32 v[166:167], v[166:167], 1.0 op_sel_hi:[1,0]
	v_pk_fma_f32 v[24:25], v[168:169], v[164:165], v[24:25]
	v_pk_add_f32 v[168:169], v[106:107], v[0:1]
	v_rcp_f32_e32 v166, v166
	v_rcp_f32_e32 v167, v167
	v_pk_mul_f32 v[168:169], v[168:169], s[2:3] op_sel_hi:[1,0]
	s_waitcnt vmcnt(12)
	v_lshlrev_b32_e32 v164, 16, v160
	v_exp_f32_e32 v168, v168
	v_exp_f32_e32 v169, v169
	v_and_b32_e32 v165, 0xffff0000, v160
	v_lshlrev_b32_e32 v160, 16, v161
	v_and_b32_e32 v161, 0xffff0000, v161
	v_pk_fma_f32 v[24:25], v[166:167], v[160:161], v[24:25]
	v_pk_add_f32 v[160:161], v[94:95], v[12:13]
	v_pk_add_f32 v[168:169], v[168:169], 1.0 op_sel_hi:[1,0]
	v_pk_mul_f32 v[160:161], v[160:161], s[2:3] op_sel_hi:[1,0]
	v_rcp_f32_e32 v168, v168
	v_exp_f32_e32 v160, v160
	v_exp_f32_e32 v161, v161
	v_rcp_f32_e32 v169, v169
	v_pk_mul_f32 v[184:185], v[184:185], s[2:3] op_sel_hi:[1,0]
	v_pk_mul_f32 v[186:187], v[186:187], s[2:3] op_sel_hi:[1,0]
	v_pk_add_f32 v[160:161], v[160:161], 1.0 op_sel_hi:[1,0]
	v_pk_fma_f32 v[22:23], v[168:169], v[164:165], v[22:23]
	v_rcp_f32_e32 v160, v160
	v_rcp_f32_e32 v161, v161
	v_cvt_pk_bf16_f32 v22, v22, v23
	v_cvt_pk_bf16_f32 v23, v24, v25
	v_lshlrev_b64 v[24:25], 11, v[152:153]
	v_lshl_add_u64 v[24:25], v[16:17], 0, v[24:25]
	global_store_dwordx2 v[24:25], v[22:23], off
	s_waitcnt vmcnt(10)
	v_lshlrev_b32_e32 v22, 16, v162
	v_and_b32_e32 v23, 0xffff0000, v162
	v_pk_add_f32 v[152:153], v[96:97], v[14:15]
	v_lshlrev_b32_e32 v24, 16, v163
	v_and_b32_e32 v25, 0xffff0000, v163
	v_pk_mul_f32 v[152:153], v[152:153], s[2:3] op_sel_hi:[1,0]
	v_pk_fma_f32 v[22:23], v[160:161], v[22:23], 0 op_sel_hi:[1,1,0]
	v_pk_add_f32 v[160:161], v[84:85], v[10:11]
	v_pk_add_f32 v[162:163], v[82:83], v[8:9]
	v_exp_f32_e32 v152, v152
	v_exp_f32_e32 v153, v153
	v_pk_mul_f32 v[160:161], v[160:161], s[2:3] op_sel_hi:[1,0]
	v_pk_mul_f32 v[162:163], v[162:163], s[2:3] op_sel_hi:[1,0]
	v_exp_f32_e32 v160, v160
	v_exp_f32_e32 v162, v162
	v_exp_f32_e32 v163, v163
	v_exp_f32_e32 v161, v161
	v_pk_add_f32 v[152:153], v[152:153], 1.0 op_sel_hi:[1,0]
	v_add_u32_e32 v164, 0x90, v20
	v_rcp_f32_e32 v152, v152
	v_rcp_f32_e32 v153, v153
	v_pk_add_f32 v[160:161], v[160:161], 1.0 op_sel_hi:[1,0]
	v_pk_add_f32 v[162:163], v[162:163], 1.0 op_sel_hi:[1,0]
	v_rcp_f32_e32 v160, v160
	v_rcp_f32_e32 v162, v162
	v_rcp_f32_e32 v163, v163
	v_rcp_f32_e32 v161, v161
	v_pk_fma_f32 v[24:25], v[152:153], v[24:25], 0 op_sel_hi:[1,1,0]
	s_waitcnt vmcnt(9)
	v_lshlrev_b32_e32 v152, 16, v156
	v_and_b32_e32 v153, 0xffff0000, v156
	v_lshlrev_b32_e32 v156, 16, v157
	v_and_b32_e32 v157, 0xffff0000, v157
	v_pk_fma_f32 v[22:23], v[162:163], v[152:153], v[22:23]
	v_pk_fma_f32 v[24:25], v[160:161], v[156:157], v[24:25]
	s_waitcnt vmcnt(6)
; __device__ __forceinline__ unsigned cvt_pk_bf16(float lo, float hi) { unsigned r; asm volatile("v_cvt_pk_bf16_f32 %0, %1, %2" : "=v"(r) : "v"(lo), "v"(hi)); return r; }
; __device__ __forceinline__ float bf_lo(unsigned w) { return __uint_as_float(w << 16); }
; __device__ __forceinline__ float bf_hi(unsigned w) { return __uint_as_float(w & 0xffff0000u); }
;     __device__ __forceinline__ void operator()(const Acc& acc, const Unit& u, int wr, int wc, int fr, int fq) const {
;     ...
;                 for (int m = 0; m < 4; ++m) { const size_t row = (size_t)(u.pm * BM + ai * HALF + wr * 64 + m * 16 + fr);
; #pragma unroll
;                     for (int gn = 0; gn < 4; ++gn) pw[0][m][gn] = *(const u32x2*)(P + row * 4096 + gn * DM + mc); }
;                 asm volatile("" ::: "memory");
; #pragma unroll
;                 for (int m = 0; m < 4; ++m) {
;                     const size_t row = (size_t)(u.pm * BM + ai * HALF + wr * 64 + m * 16 + fr);
;                     f32x4 sum = {0.f, 0.f, 0.f, 0.f};
; #pragma unroll
;                     for (int bj = 0; bj < 2; ++bj)
; #pragma unroll
;                         for (int n = 0; n < 2; ++n) {
;                             const int gn = 2 * bj + n;
;                             const u32x2 w2 = pw[0][m][gn];
;                             const f32x4 pv = {bf_lo(w2.x), bf_hi(w2.x), bf_lo(w2.y), bf_hi(w2.y)};
;                             sum += sigmoid4(acc[ai][bj][m][n] + gb[gn]) * pv;
;                         }
;                     u32x2 w; w.x = cvt_pk_bf16(sum[0], sum[1]); w.y = cvt_pk_bf16(sum[2], sum[3]);
;                     *(u32x2*)(MG + row * DM + mc) = w;
	v_lshlrev_b32_e32 v152, 16, v158
	v_and_b32_e32 v153, 0xffff0000, v158
	v_lshlrev_b32_e32 v156, 16, v159
	v_and_b32_e32 v157, 0xffff0000, v159
	v_pk_add_f32 v[158:159], v[100:101], v[6:7]
	v_pk_add_f32 v[160:161], v[98:99], v[4:5]
	v_pk_mul_f32 v[158:159], v[158:159], s[2:3] op_sel_hi:[1,0]
	v_pk_mul_f32 v[160:161], v[160:161], s[2:3] op_sel_hi:[1,0]
	v_exp_f32_e32 v158, v158
	v_exp_f32_e32 v159, v159
	v_exp_f32_e32 v160, v160
	v_exp_f32_e32 v161, v161
	v_ashrrev_i32_e32 v165, 31, v164
	v_pk_add_f32 v[158:159], v[158:159], 1.0 op_sel_hi:[1,0]
	v_exp_f32_e32 v186, v186
	v_rcp_f32_e32 v158, v158
	v_rcp_f32_e32 v159, v159
	v_pk_add_f32 v[160:161], v[160:161], 1.0 op_sel_hi:[1,0]
	v_exp_f32_e32 v187, v187
	v_rcp_f32_e32 v160, v160
	v_pk_fma_f32 v[24:25], v[158:159], v[156:157], v[24:25]
	v_pk_add_f32 v[156:157], v[92:93], v[2:3]
	v_pk_add_f32 v[158:159], v[90:91], v[0:1]
	v_pk_mul_f32 v[156:157], v[156:157], s[2:3] op_sel_hi:[1,0]
	v_pk_mul_f32 v[158:159], v[158:159], s[2:3] op_sel_hi:[1,0]
	v_exp_f32_e32 v156, v156
	v_exp_f32_e32 v158, v158
	v_exp_f32_e32 v159, v159
	v_exp_f32_e32 v157, v157
	v_rcp_f32_e32 v161, v161
	v_exp_f32_e32 v184, v184
	v_pk_add_f32 v[158:159], v[158:159], 1.0 op_sel_hi:[1,0]
	v_pk_add_f32 v[156:157], v[156:157], 1.0 op_sel_hi:[1,0]
	v_rcp_f32_e32 v158, v158
	v_rcp_f32_e32 v159, v159
	v_rcp_f32_e32 v156, v156
	v_rcp_f32_e32 v157, v157
	v_pk_fma_f32 v[22:23], v[160:161], v[152:153], v[22:23]
	s_waitcnt vmcnt(5)
	v_lshlrev_b32_e32 v152, 16, v154
	v_and_b32_e32 v153, 0xffff0000, v154
	v_lshlrev_b32_e32 v154, 16, v155
	v_and_b32_e32 v155, 0xffff0000, v155
	v_pk_fma_f32 v[24:25], v[156:157], v[154:155], v[24:25]
	v_pk_fma_f32 v[22:23], v[158:159], v[152:153], v[22:23]
	v_add_u32_e32 v154, 0xa0, v20
	v_cvt_pk_bf16_f32 v22, v22, v23
	v_cvt_pk_bf16_f32 v23, v24, v25
	v_lshlrev_b64 v[24:25], 11, v[150:151]
	v_lshl_add_u64 v[24:25], v[16:17], 0, v[24:25]
	global_store_dwordx2 v[24:25], v[22:23], off
	v_lshlrev_b64 v[22:23], 13, v[174:175]
	v_lshl_add_u64 v[22:23], v[18:19], 0, v[22:23]
	s_waitcnt vmcnt(4)
	v_mov_b64_e32 v[24:25], v[192:193]
	v_mov_b64_e32 v[180:181], v[194:195]
	v_add_co_u32_e32 v22, vcc, s0, v22
	v_ashrrev_i32_e32 v155, 31, v154
	s_nop 0
	v_addc_co_u32_e32 v23, vcc, 0, v23, vcc
	v_mov_b64_e32 v[182:183], v[196:197]
	v_mov_b64_e32 v[178:179], v[198:199]
	v_lshlrev_b64 v[22:23], 13, v[164:165]
	v_lshl_add_u64 v[22:23], v[18:19], 0, v[22:23]
	v_mov_b64_e32 v[176:177], v[200:201]
	v_mov_b64_e32 v[172:173], v[202:203]
	v_add_co_u32_e32 v22, vcc, s0, v22
	v_exp_f32_e32 v185, v185
	s_nop 0
	v_addc_co_u32_e32 v23, vcc, 0, v23, vcc
	v_mov_b64_e32 v[170:171], v[204:205]
	v_mov_b64_e32 v[168:169], v[206:207]
	v_pk_mul_f32 v[188:189], v[188:189], s[2:3] op_sel_hi:[1,0]
	v_lshlrev_b64 v[22:23], 13, v[154:155]
	v_exp_f32_e32 v188, v188
	v_exp_f32_e32 v189, v189
	v_lshl_add_u64 v[22:23], v[18:19], 0, v[22:23]
	v_mov_b64_e32 v[166:167], v[208:209]
	v_mov_b64_e32 v[162:163], v[210:211]
	v_pk_add_f32 v[184:185], v[184:185], 1.0 op_sel_hi:[1,0]
	v_pk_add_f32 v[186:187], v[186:187], 1.0 op_sel_hi:[1,0]
	v_add_co_u32_e32 v22, vcc, s0, v22
	v_add_u32_e32 v20, 0xb0, v20
	v_rcp_f32_e32 v186, v186
	v_rcp_f32_e32 v187, v187
	v_rcp_f32_e32 v184, v184
	v_rcp_f32_e32 v185, v185
	v_pk_add_f32 v[188:189], v[188:189], 1.0 op_sel_hi:[1,0]
	v_addc_co_u32_e32 v23, vcc, 0, v23, vcc
	v_ashrrev_i32_e32 v21, 31, v20
	v_rcp_f32_e32 v188, v188
	v_rcp_f32_e32 v189, v189
	v_mov_b64_e32 v[160:161], v[212:213]
	v_mov_b64_e32 v[158:159], v[214:215]
	v_lshlrev_b64 v[22:23], 13, v[20:21]
	v_lshl_add_u64 v[18:19], v[18:19], 0, v[22:23]
	v_mov_b64_e32 v[156:157], v[216:217]
	v_mov_b64_e32 v[152:153], v[218:219]
	v_add_co_u32_e32 v18, vcc, s0, v18
	s_mov_b64 s[0:1], 0
	s_nop 0
	v_addc_co_u32_e32 v19, vcc, 0, v19, vcc
	v_mov_b64_e32 v[150:151], v[220:221]
	s_nop 0
	v_mov_b64_e32 v[18:19], v[224:225]
	v_lshlrev_b32_e32 v22, 16, v24
	v_and_b32_e32 v23, 0xffff0000, v24
	v_lshlrev_b32_e32 v24, 16, v25
	v_and_b32_e32 v25, 0xffff0000, v25
	v_pk_fma_f32 v[24:25], v[184:185], v[24:25], 0 op_sel_hi:[1,1,0]
	v_pk_fma_f32 v[22:23], v[186:187], v[22:23], 0 op_sel_hi:[1,1,0]
	v_lshlrev_b32_e32 v184, 16, v180
	v_and_b32_e32 v185, 0xffff0000, v180
	v_pk_add_f32 v[186:187], v[72:73], v[10:11]
	v_pk_fma_f32 v[22:23], v[188:189], v[184:185], v[22:23]
	v_pk_mul_f32 v[186:187], v[186:187], s[2:3] op_sel_hi:[1,0]
	v_pk_add_f32 v[184:185], v[88:89], v[6:7]
	v_exp_f32_e32 v186, v186
	v_exp_f32_e32 v187, v187
	v_pk_mul_f32 v[184:185], v[184:185], s[2:3] op_sel_hi:[1,0]
	v_lshlrev_b32_e32 v180, 16, v181
	v_exp_f32_e32 v184, v184
	v_exp_f32_e32 v185, v185
	v_pk_add_f32 v[186:187], v[186:187], 1.0 op_sel_hi:[1,0]
	v_and_b32_e32 v181, 0xffff0000, v181
	v_rcp_f32_e32 v186, v186
	v_rcp_f32_e32 v187, v187
	v_pk_add_f32 v[184:185], v[184:185], 1.0 op_sel_hi:[1,0]
	v_pk_fma_f32 v[24:25], v[186:187], v[180:181], v[24:25]
	v_rcp_f32_e32 v184, v184
	v_rcp_f32_e32 v185, v185
	v_lshlrev_b32_e32 v180, 16, v182
	v_and_b32_e32 v181, 0xffff0000, v182
	v_lshlrev_b32_e32 v182, 16, v183
	v_and_b32_e32 v183, 0xffff0000, v183
	v_pk_add_f32 v[186:187], v[86:87], v[4:5]
	v_pk_fma_f32 v[24:25], v[184:185], v[182:183], v[24:25]
	v_pk_mul_f32 v[186:187], v[186:187], s[2:3] op_sel_hi:[1,0]
	v_pk_add_f32 v[182:183], v[76:77], v[2:3]
	v_pk_add_f32 v[184:185], v[74:75], v[0:1]
	v_exp_f32_e32 v186, v186
	v_exp_f32_e32 v187, v187
	v_pk_mul_f32 v[182:183], v[182:183], s[2:3] op_sel_hi:[1,0]
	v_pk_mul_f32 v[184:185], v[184:185], s[2:3] op_sel_hi:[1,0]
	v_exp_f32_e32 v182, v182
	v_exp_f32_e32 v184, v184
	v_exp_f32_e32 v185, v185
	v_exp_f32_e32 v183, v183
	v_pk_add_f32 v[186:187], v[186:187], 1.0 op_sel_hi:[1,0]
; __device__ __forceinline__ unsigned cvt_pk_bf16(float lo, float hi) { unsigned r; asm volatile("v_cvt_pk_bf16_f32 %0, %1, %2" : "=v"(r) : "v"(lo), "v"(hi)); return r; }
; __device__ __forceinline__ float bf_lo(unsigned w) { return __uint_as_float(w << 16); }
; __device__ __forceinline__ float bf_hi(unsigned w) { return __uint_as_float(w & 0xffff0000u); }
;     __device__ __forceinline__ void operator()(const Acc& acc, const Unit& u, int wr, int wc, int fr, int fq) const {
;     ...
; #pragma unroll
;                 for (int m = 0; m < 4; ++m) {
;                     const size_t row = (size_t)(u.pm * BM + ai * HALF + wr * 64 + m * 16 + fr);
;                     f32x4 sum = {0.f, 0.f, 0.f, 0.f};
; #pragma unroll
;                     for (int bj = 0; bj < 2; ++bj)
; #pragma unroll
;                         for (int n = 0; n < 2; ++n) {
;                             const int gn = 2 * bj + n;
;                             const u32x2 w2 = pw[0][m][gn];
;                             const f32x4 pv = {bf_lo(w2.x), bf_hi(w2.x), bf_lo(w2.y), bf_hi(w2.y)};
;                             sum += sigmoid4(acc[ai][bj][m][n] + gb[gn]) * pv;
;                         }
;                     u32x2 w; w.x = cvt_pk_bf16(sum[0], sum[1]); w.y = cvt_pk_bf16(sum[2], sum[3]);
;                     *(u32x2*)(MG + row * DM + mc) = w;
	v_pk_add_f32 v[184:185], v[184:185], 1.0 op_sel_hi:[1,0]
	v_rcp_f32_e32 v186, v186
	v_rcp_f32_e32 v187, v187
	v_pk_add_f32 v[182:183], v[182:183], 1.0 op_sel_hi:[1,0]
	v_rcp_f32_e32 v184, v184
	v_rcp_f32_e32 v185, v185
	v_rcp_f32_e32 v182, v182
	v_rcp_f32_e32 v183, v183
	v_pk_fma_f32 v[22:23], v[186:187], v[180:181], v[22:23]
	v_lshlrev_b32_e32 v180, 16, v178
	v_and_b32_e32 v181, 0xffff0000, v178
	v_lshlrev_b32_e32 v178, 16, v179
	v_and_b32_e32 v179, 0xffff0000, v179
	v_pk_fma_f32 v[24:25], v[182:183], v[178:179], v[24:25]
	v_pk_fma_f32 v[22:23], v[184:185], v[180:181], v[22:23]
	v_pk_add_f32 v[178:179], v[54:55], v[8:9]
	v_cvt_pk_bf16_f32 v22, v22, v23
	v_cvt_pk_bf16_f32 v23, v24, v25
	v_lshlrev_b64 v[24:25], 11, v[174:175]
	v_lshl_add_u64 v[24:25], v[16:17], 0, v[24:25]
	global_store_dwordx2 v[24:25], v[22:23], off
	v_lshlrev_b32_e32 v22, 16, v176
	v_and_b32_e32 v23, 0xffff0000, v176
	v_lshlrev_b32_e32 v24, 16, v177
	v_and_b32_e32 v25, 0xffff0000, v177
	v_pk_add_f32 v[176:177], v[62:63], v[12:13]
	v_pk_add_f32 v[174:175], v[64:65], v[14:15]
	v_pk_mul_f32 v[176:177], v[176:177], s[2:3] op_sel_hi:[1,0]
	v_pk_mul_f32 v[174:175], v[174:175], s[2:3] op_sel_hi:[1,0]
	v_exp_f32_e32 v176, v176
	v_exp_f32_e32 v177, v177
	v_exp_f32_e32 v174, v174
	v_exp_f32_e32 v175, v175
	v_pk_mul_f32 v[178:179], v[178:179], s[2:3] op_sel_hi:[1,0]
	v_pk_add_f32 v[176:177], v[176:177], 1.0 op_sel_hi:[1,0]
	v_exp_f32_e32 v178, v178
	v_rcp_f32_e32 v176, v176
	v_rcp_f32_e32 v177, v177
	v_exp_f32_e32 v179, v179
	v_pk_add_f32 v[174:175], v[174:175], 1.0 op_sel_hi:[1,0]
	v_pk_fma_f32 v[22:23], v[176:177], v[22:23], 0 op_sel_hi:[1,1,0]
	v_pk_add_f32 v[176:177], v[56:57], v[10:11]
	v_rcp_f32_e32 v174, v174
	v_pk_mul_f32 v[176:177], v[176:177], s[2:3] op_sel_hi:[1,0]
	v_rcp_f32_e32 v175, v175
	v_exp_f32_e32 v176, v176
	v_exp_f32_e32 v177, v177
	v_pk_add_f32 v[178:179], v[178:179], 1.0 op_sel_hi:[1,0]
	v_pk_fma_f32 v[24:25], v[174:175], v[24:25], 0 op_sel_hi:[1,1,0]
	v_rcp_f32_e32 v178, v178
	v_pk_add_f32 v[176:177], v[176:177], 1.0 op_sel_hi:[1,0]
	v_rcp_f32_e32 v179, v179
	v_rcp_f32_e32 v176, v176
	v_rcp_f32_e32 v177, v177
	v_lshlrev_b32_e32 v174, 16, v172
	v_and_b32_e32 v175, 0xffff0000, v172
	v_lshlrev_b32_e32 v172, 16, v173
	v_and_b32_e32 v173, 0xffff0000, v173
	v_pk_fma_f32 v[22:23], v[178:179], v[174:175], v[22:23]
	v_pk_fma_f32 v[24:25], v[176:177], v[172:173], v[24:25]
	v_pk_add_f32 v[174:175], v[68:69], v[6:7]
	v_pk_add_f32 v[176:177], v[66:67], v[4:5]
	v_pk_mul_f32 v[174:175], v[174:175], s[2:3] op_sel_hi:[1,0]
	v_pk_mul_f32 v[176:177], v[176:177], s[2:3] op_sel_hi:[1,0]
	v_exp_f32_e32 v174, v174
	v_exp_f32_e32 v176, v176
	v_exp_f32_e32 v177, v177
	v_exp_f32_e32 v175, v175
	v_lshlrev_b32_e32 v172, 16, v170
	v_and_b32_e32 v173, 0xffff0000, v170
	v_pk_add_f32 v[176:177], v[176:177], 1.0 op_sel_hi:[1,0]
	v_pk_add_f32 v[174:175], v[174:175], 1.0 op_sel_hi:[1,0]
	v_rcp_f32_e32 v176, v176
	v_rcp_f32_e32 v177, v177
	v_rcp_f32_e32 v174, v174
	v_rcp_f32_e32 v175, v175
	v_lshlrev_b32_e32 v170, 16, v171
	v_and_b32_e32 v171, 0xffff0000, v171
	v_pk_fma_f32 v[22:23], v[176:177], v[172:173], v[22:23]
	v_pk_fma_f32 v[24:25], v[174:175], v[170:171], v[24:25]
	v_pk_add_f32 v[172:173], v[60:61], v[2:3]
	v_pk_add_f32 v[174:175], v[58:59], v[0:1]
	v_pk_mul_f32 v[172:173], v[172:173], s[2:3] op_sel_hi:[1,0]
	v_pk_mul_f32 v[174:175], v[174:175], s[2:3] op_sel_hi:[1,0]
	v_exp_f32_e32 v172, v172
	v_exp_f32_e32 v174, v174
	v_exp_f32_e32 v175, v175
	v_exp_f32_e32 v173, v173
	v_lshlrev_b32_e32 v170, 16, v168
	v_and_b32_e32 v171, 0xffff0000, v168
	v_pk_add_f32 v[174:175], v[174:175], 1.0 op_sel_hi:[1,0]
	v_pk_add_f32 v[172:173], v[172:173], 1.0 op_sel_hi:[1,0]
	v_rcp_f32_e32 v174, v174
	v_rcp_f32_e32 v175, v175
	v_rcp_f32_e32 v172, v172
	v_rcp_f32_e32 v173, v173
	v_lshlrev_b32_e32 v168, 16, v169
	v_and_b32_e32 v169, 0xffff0000, v169
	v_pk_fma_f32 v[22:23], v[174:175], v[170:171], v[22:23]
	v_pk_fma_f32 v[24:25], v[172:173], v[168:169], v[24:25]
	v_cvt_pk_bf16_f32 v22, v22, v23
	v_pk_add_f32 v[168:169], v[38:39], v[8:9]
	v_cvt_pk_bf16_f32 v23, v24, v25
	v_lshlrev_b64 v[24:25], 11, v[164:165]
	v_lshl_add_u64 v[24:25], v[16:17], 0, v[24:25]
	global_store_dwordx2 v[24:25], v[22:23], off
	v_lshlrev_b32_e32 v22, 16, v166
	v_and_b32_e32 v23, 0xffff0000, v166
	v_lshlrev_b32_e32 v24, 16, v167
	v_and_b32_e32 v25, 0xffff0000, v167
	v_pk_add_f32 v[166:167], v[46:47], v[12:13]
	v_pk_add_f32 v[164:165], v[48:49], v[14:15]
	v_pk_mul_f32 v[166:167], v[166:167], s[2:3] op_sel_hi:[1,0]
	v_pk_mul_f32 v[164:165], v[164:165], s[2:3] op_sel_hi:[1,0]
	v_exp_f32_e32 v166, v166
	v_exp_f32_e32 v167, v167
	v_exp_f32_e32 v164, v164
	v_exp_f32_e32 v165, v165
	v_pk_mul_f32 v[168:169], v[168:169], s[2:3] op_sel_hi:[1,0]
	v_pk_add_f32 v[166:167], v[166:167], 1.0 op_sel_hi:[1,0]
	v_exp_f32_e32 v168, v168
	v_rcp_f32_e32 v166, v166
	v_rcp_f32_e32 v167, v167
	v_exp_f32_e32 v169, v169
	v_pk_add_f32 v[164:165], v[164:165], 1.0 op_sel_hi:[1,0]
	v_pk_add_f32 v[14:15], v[32:33], v[14:15]
	v_pk_fma_f32 v[22:23], v[166:167], v[22:23], 0 op_sel_hi:[1,1,0]
	v_pk_add_f32 v[166:167], v[40:41], v[10:11]
	v_rcp_f32_e32 v164, v164
	v_pk_mul_f32 v[166:167], v[166:167], s[2:3] op_sel_hi:[1,0]
	v_rcp_f32_e32 v165, v165
	v_exp_f32_e32 v166, v166
	v_exp_f32_e32 v167, v167
	v_pk_add_f32 v[168:169], v[168:169], 1.0 op_sel_hi:[1,0]
; __device__ __forceinline__ unsigned cvt_pk_bf16(float lo, float hi) { unsigned r; asm volatile("v_cvt_pk_bf16_f32 %0, %1, %2" : "=v"(r) : "v"(lo), "v"(hi)); return r; }
; __device__ __forceinline__ float bf_lo(unsigned w) { return __uint_as_float(w << 16); }
; __device__ __forceinline__ float bf_hi(unsigned w) { return __uint_as_float(w & 0xffff0000u); }
;     __device__ __forceinline__ void operator()(const Acc& acc, const Unit& u, int wr, int wc, int fr, int fq) const {
;     ...
; #pragma unroll
;                 for (int m = 0; m < 4; ++m) {
;                     const size_t row = (size_t)(u.pm * BM + ai * HALF + wr * 64 + m * 16 + fr);
;                     f32x4 sum = {0.f, 0.f, 0.f, 0.f};
; #pragma unroll
;                     for (int bj = 0; bj < 2; ++bj)
; #pragma unroll
;                         for (int n = 0; n < 2; ++n) {
;                             const int gn = 2 * bj + n;
;                             const u32x2 w2 = pw[0][m][gn];
;                             const f32x4 pv = {bf_lo(w2.x), bf_hi(w2.x), bf_lo(w2.y), bf_hi(w2.y)};
;                             sum += sigmoid4(acc[ai][bj][m][n] + gb[gn]) * pv;
;                         }
;                     u32x2 w; w.x = cvt_pk_bf16(sum[0], sum[1]); w.y = cvt_pk_bf16(sum[2], sum[3]);
;                     *(u32x2*)(MG + row * DM + mc) = w;
	v_pk_fma_f32 v[24:25], v[164:165], v[24:25], 0 op_sel_hi:[1,1,0]
	v_rcp_f32_e32 v168, v168
	v_pk_add_f32 v[166:167], v[166:167], 1.0 op_sel_hi:[1,0]
	v_rcp_f32_e32 v169, v169
	v_rcp_f32_e32 v166, v166
	v_rcp_f32_e32 v167, v167
	v_lshlrev_b32_e32 v164, 16, v162
	v_and_b32_e32 v165, 0xffff0000, v162
	v_lshlrev_b32_e32 v162, 16, v163
	v_and_b32_e32 v163, 0xffff0000, v163
	v_pk_fma_f32 v[22:23], v[168:169], v[164:165], v[22:23]
	v_pk_fma_f32 v[24:25], v[166:167], v[162:163], v[24:25]
	v_pk_add_f32 v[164:165], v[52:53], v[6:7]
	v_pk_add_f32 v[166:167], v[50:51], v[4:5]
	v_pk_mul_f32 v[164:165], v[164:165], s[2:3] op_sel_hi:[1,0]
	v_pk_mul_f32 v[166:167], v[166:167], s[2:3] op_sel_hi:[1,0]
	v_exp_f32_e32 v164, v164
	v_exp_f32_e32 v166, v166
	v_exp_f32_e32 v167, v167
	v_exp_f32_e32 v165, v165
	v_lshlrev_b32_e32 v162, 16, v160
	v_and_b32_e32 v163, 0xffff0000, v160
	v_pk_add_f32 v[166:167], v[166:167], 1.0 op_sel_hi:[1,0]
	v_pk_add_f32 v[164:165], v[164:165], 1.0 op_sel_hi:[1,0]
	v_rcp_f32_e32 v166, v166
	v_rcp_f32_e32 v167, v167
	v_rcp_f32_e32 v164, v164
	v_rcp_f32_e32 v165, v165
	v_lshlrev_b32_e32 v160, 16, v161
	v_and_b32_e32 v161, 0xffff0000, v161
	v_pk_fma_f32 v[22:23], v[166:167], v[162:163], v[22:23]
	v_pk_fma_f32 v[24:25], v[164:165], v[160:161], v[24:25]
	v_pk_add_f32 v[162:163], v[44:45], v[2:3]
	v_pk_add_f32 v[164:165], v[42:43], v[0:1]
	v_pk_mul_f32 v[162:163], v[162:163], s[2:3] op_sel_hi:[1,0]
	v_pk_mul_f32 v[164:165], v[164:165], s[2:3] op_sel_hi:[1,0]
	v_exp_f32_e32 v162, v162
	v_exp_f32_e32 v164, v164
	v_exp_f32_e32 v165, v165
	v_exp_f32_e32 v163, v163
	v_pk_add_f32 v[12:13], v[30:31], v[12:13]
	v_pk_mul_f32 v[14:15], v[14:15], s[2:3] op_sel_hi:[1,0]
	v_pk_mul_f32 v[12:13], v[12:13], s[2:3] op_sel_hi:[1,0]
	v_pk_add_f32 v[10:11], v[228:229], v[10:11]
	v_pk_add_f32 v[8:9], v[226:227], v[8:9]
	v_pk_add_f32 v[162:163], v[162:163], 1.0 op_sel_hi:[1,0]
	v_pk_add_f32 v[164:165], v[164:165], 1.0 op_sel_hi:[1,0]
	v_exp_f32_e32 v12, v12
	v_exp_f32_e32 v13, v13
	v_exp_f32_e32 v14, v14
	v_exp_f32_e32 v15, v15
	v_pk_mul_f32 v[10:11], v[10:11], s[2:3] op_sel_hi:[1,0]
	v_pk_mul_f32 v[8:9], v[8:9], s[2:3] op_sel_hi:[1,0]
	v_pk_add_f32 v[6:7], v[36:37], v[6:7]
	v_pk_add_f32 v[4:5], v[34:35], v[4:5]
	v_rcp_f32_e32 v164, v164
	v_rcp_f32_e32 v165, v165
	v_rcp_f32_e32 v162, v162
	v_rcp_f32_e32 v163, v163
	v_exp_f32_e32 v8, v8
	v_exp_f32_e32 v9, v9
	v_exp_f32_e32 v10, v10
	v_exp_f32_e32 v11, v11
	v_pk_mul_f32 v[6:7], v[6:7], s[2:3] op_sel_hi:[1,0]
	v_pk_mul_f32 v[4:5], v[4:5], s[2:3] op_sel_hi:[1,0]
	v_pk_add_f32 v[2:3], v[28:29], v[2:3]
	v_pk_add_f32 v[0:1], v[26:27], v[0:1]
	v_exp_f32_e32 v4, v4
	v_exp_f32_e32 v5, v5
	v_exp_f32_e32 v6, v6
	v_exp_f32_e32 v7, v7
	v_pk_mul_f32 v[2:3], v[2:3], s[2:3] op_sel_hi:[1,0]
	v_pk_mul_f32 v[0:1], v[0:1], s[2:3] op_sel_hi:[1,0]
	v_exp_f32_e32 v2, v2
	v_exp_f32_e32 v0, v0
	v_exp_f32_e32 v1, v1
	v_exp_f32_e32 v3, v3
	v_lshlrev_b32_e32 v160, 16, v158
	v_and_b32_e32 v161, 0xffff0000, v158
	v_lshlrev_b32_e32 v158, 16, v159
	v_and_b32_e32 v159, 0xffff0000, v159
	v_pk_add_f32 v[14:15], v[14:15], 1.0 op_sel_hi:[1,0]
	v_pk_add_f32 v[12:13], v[12:13], 1.0 op_sel_hi:[1,0]
	v_pk_fma_f32 v[24:25], v[162:163], v[158:159], v[24:25]
	v_pk_fma_f32 v[22:23], v[164:165], v[160:161], v[22:23]
	v_rcp_f32_e32 v12, v12
	v_rcp_f32_e32 v13, v13
	v_rcp_f32_e32 v14, v14
	v_rcp_f32_e32 v15, v15
	v_pk_add_f32 v[10:11], v[10:11], 1.0 op_sel_hi:[1,0]
	v_pk_add_f32 v[8:9], v[8:9], 1.0 op_sel_hi:[1,0]
	v_cvt_pk_bf16_f32 v22, v22, v23
	v_cvt_pk_bf16_f32 v23, v24, v25
	v_lshlrev_b64 v[24:25], 11, v[154:155]
	v_rcp_f32_e32 v8, v8
	v_rcp_f32_e32 v9, v9
	v_rcp_f32_e32 v10, v10
	v_rcp_f32_e32 v11, v11
	v_pk_add_f32 v[6:7], v[6:7], 1.0 op_sel_hi:[1,0]
	v_pk_add_f32 v[4:5], v[4:5], 1.0 op_sel_hi:[1,0]
	v_lshl_add_u64 v[24:25], v[16:17], 0, v[24:25]
	v_rcp_f32_e32 v4, v4
	v_rcp_f32_e32 v5, v5
	v_rcp_f32_e32 v6, v6
	v_rcp_f32_e32 v7, v7
	v_pk_add_f32 v[2:3], v[2:3], 1.0 op_sel_hi:[1,0]
	v_pk_add_f32 v[0:1], v[0:1], 1.0 op_sel_hi:[1,0]
	global_store_dwordx2 v[24:25], v[22:23], off
	v_lshlrev_b32_e32 v22, 16, v156
	v_and_b32_e32 v23, 0xffff0000, v156
	v_lshlrev_b32_e32 v24, 16, v157
	v_and_b32_e32 v25, 0xffff0000, v157
	v_rcp_f32_e32 v0, v0
	v_rcp_f32_e32 v1, v1
	v_rcp_f32_e32 v2, v2
	v_rcp_f32_e32 v3, v3
	v_pk_fma_f32 v[14:15], v[14:15], v[24:25], 0 op_sel_hi:[1,1,0]
	v_pk_fma_f32 v[12:13], v[12:13], v[22:23], 0 op_sel_hi:[1,1,0]
	v_lshlrev_b32_e32 v22, 16, v152
	v_and_b32_e32 v23, 0xffff0000, v152
	v_lshlrev_b32_e32 v24, 16, v153
	v_and_b32_e32 v25, 0xffff0000, v153
	v_pk_fma_f32 v[8:9], v[8:9], v[22:23], v[12:13]
	v_pk_fma_f32 v[10:11], v[10:11], v[24:25], v[14:15]
	v_lshlrev_b32_e32 v12, 16, v150
	v_and_b32_e32 v13, 0xffff0000, v150
	v_lshlrev_b32_e32 v14, 16, v151
	v_and_b32_e32 v15, 0xffff0000, v151
	v_pk_fma_f32 v[6:7], v[6:7], v[14:15], v[10:11]
	v_pk_fma_f32 v[4:5], v[4:5], v[12:13], v[8:9]
	v_lshlrev_b32_e32 v8, 16, v18
	v_and_b32_e32 v9, 0xffff0000, v18
	v_lshlrev_b32_e32 v10, 16, v19
	v_and_b32_e32 v11, 0xffff0000, v19
	v_pk_fma_f32 v[2:3], v[2:3], v[10:11], v[6:7]
	v_pk_fma_f32 v[0:1], v[0:1], v[8:9], v[4:5]
	s_nop 0
	v_cvt_pk_bf16_f32 v0, v0, v1
	v_cvt_pk_bf16_f32 v1, v2, v3
	v_lshlrev_b64 v[2:3], 11, v[20:21]
	v_lshl_add_u64 v[2:3], v[16:17], 0, v[2:3]
	global_store_dwordx2 v[2:3], v[0:1], off
